# P7 GEMM K-loop: per-cluster s_setprio flips removed, one static s_setprio 1 for waves 4-7 (the half that runs one barrier behind) before the loop
# speedup vs baseline: 1.0095x; 1.0095x over previous
;     __host__ __device__ bool next(int i, Unit& u) const { const long L = (long)i * so.G + so.c; if (L < so.nwg) return so.next(i, u); if (L >= so.nwg + extra) return false; u.pm = so.nM + (int)(L - so.nwg); u.pn = so.nN - 1; return true; }
; #define PG8_STAGE(bufoff, gbase, voff) do { _Pragma("unroll") for (int _i = 0; _i < 2; ++_i) \
;         __builtin_amdgcn_global_load_lds((const unsigned*)((const char*)(gbase) + (voff)[_i]), (PG8_LAS unsigned*)(lds + (bufoff) + ldsw + _i * 8192), 16, 0, 0); } while (0)
; #define PG8_LDA(dst, b, h) do { _Pragma("unroll") for (int m = 0; m < 4; ++m) _Pragma("unroll") for (int k = 0; k < 2; ++k) dst[m][k] = *(const PG8_LAS bf16x8*)(lds + PG8_SA(b, h) + aoff + m * 2048 + k * 1024); } while (0)
; #define PG8_LDB(dst, b, h) do { _Pragma("unroll") for (int n = 0; n < 2; ++n) _Pragma("unroll") for (int k = 0; k < 2; ++k) dst[n][k] = *(const PG8_LAS bf16x8*)(lds + PG8_SB(b, h) + boff + n * 2048 + k * 1024); } while (0)
; #define PG8_SCHED __builtin_amdgcn_sched_barrier(0)
; template <class Epi, class Sched, bool ALIGN_EPI = false, bool SP2 = false>
; __device__ __forceinline__ void gemm_phase(PG8_LAS unsigned char* lds, const Gemm g, const Sched& S, const Epi& E) {
;     ...
;     for (;;) {
;         const bool has_next = S.next(ui + 1, nxt);
;         const char* nA = has_next ? (const char*)g.A + (size_t)nxt.pm * tstepA : cA; const char* nB = has_next ? (const char*)g.Bt + (size_t)nxt.pn * tstep : cB;
;         for (int t = 0; t < nt; t += 2) {
;             const bool last = (t == nt - 2);
;             const char* a1 = cA + (size_t)(t + 1) * kstep;
;             const char* a2 = last ? nA : cA + (size_t)(t + 2) * kstep; const char* b2 = last ? nB : cB + (size_t)(t + 2) * kstep;
;             const char* a3 = a2 + kstep; const char* b3 = b2 + kstep;
;             if (last && has_next) S.a_ready(nxt);
;             if constexpr (SP2) {
;             PG8_LDB(B0, 0, 0); PG8_LDB(B1, 0, 1); PG8_SCHED; PG8_LDA(At, 0, 0); PG8_STAGE(PG8_SA(1, 1), a1 + hstepA, voffA);
.LBB0_582:
	s_ashr_i32 s27, s26, 31
	s_lshl_b64 s[16:17], s[26:27], 20
	s_add_u32 s28, s36, s16
	s_addc_u32 s29, s37, s17
	s_and_b64 s[16:17], s[8:9], exec
	s_cselect_b32 s27, s29, s11
	s_cselect_b32 s62, s28, s10
	s_ashr_i32 s25, s24, 31
	s_lshl_b64 s[16:17], s[24:25], 20
	s_add_u32 s30, s38, s16
	s_addc_u32 s31, s39, s17
	s_and_b64 s[16:17], s[8:9], exec
	s_cselect_b32 s25, s31, s13
	s_cselect_b32 s91, s30, s12
	s_add_u32 s10, s10, 0x80080
	s_addc_u32 s11, s11, 0
	s_add_u32 vcc_lo, s12, 0x100
	v_mov_b32_e32 v0, 0
	s_addc_u32 vcc_hi, s13, 0
	s_mov_b32 s16, -2
	v_mov_b32_e32 v1, v0
	v_mov_b32_e32 v2, v0
	v_mov_b32_e32 v3, v0
	v_mov_b32_e32 v4, v0
	v_mov_b32_e32 v5, v0
	v_mov_b32_e32 v6, v0
	v_mov_b32_e32 v7, v0
	v_mov_b32_e32 v16, v0
	v_mov_b32_e32 v17, v0
	v_mov_b32_e32 v18, v0
	v_mov_b32_e32 v19, v0
	v_mov_b32_e32 v20, v0
	v_mov_b32_e32 v21, v0
	v_mov_b32_e32 v22, v0
	v_mov_b32_e32 v23, v0
	v_mov_b32_e32 v32, v0
	v_mov_b32_e32 v33, v0
	v_mov_b32_e32 v34, v0
	v_mov_b32_e32 v35, v0
	v_mov_b32_e32 v36, v0
	v_mov_b32_e32 v37, v0
	v_mov_b32_e32 v38, v0
	v_mov_b32_e32 v39, v0
	v_mov_b32_e32 v48, v0
	v_mov_b32_e32 v49, v0
	v_mov_b32_e32 v50, v0
	v_mov_b32_e32 v51, v0
	v_mov_b32_e32 v52, v0
	v_mov_b32_e32 v53, v0
	v_mov_b32_e32 v54, v0
	v_mov_b32_e32 v55, v0
	v_mov_b32_e32 v8, v0
	v_mov_b32_e32 v9, v0
	v_mov_b32_e32 v10, v0
	v_mov_b32_e32 v11, v0
	v_mov_b32_e32 v12, v0
	v_mov_b32_e32 v13, v0
	v_mov_b32_e32 v14, v0
	v_mov_b32_e32 v15, v0
	v_mov_b32_e32 v24, v0
	v_mov_b32_e32 v25, v0
	v_mov_b32_e32 v26, v0
	v_mov_b32_e32 v27, v0
	v_mov_b32_e32 v28, v0
	v_mov_b32_e32 v29, v0
	v_mov_b32_e32 v30, v0
	v_mov_b32_e32 v31, v0
	v_mov_b32_e32 v40, v0
	v_mov_b32_e32 v41, v0
	v_mov_b32_e32 v42, v0
	v_mov_b32_e32 v43, v0
	v_mov_b32_e32 v44, v0
	v_mov_b32_e32 v45, v0
	v_mov_b32_e32 v46, v0
	v_mov_b32_e32 v47, v0
	v_mov_b32_e32 v56, v0
	v_mov_b32_e32 v57, v0
	v_mov_b32_e32 v58, v0
	v_mov_b32_e32 v59, v0
	v_mov_b32_e32 v60, v0
	v_mov_b32_e32 v61, v0
	v_mov_b32_e32 v62, v0
	v_mov_b32_e32 v63, v0
	v_mov_b32_e32 v64, v0
	v_mov_b32_e32 v65, v0
	v_mov_b32_e32 v66, v0
	v_mov_b32_e32 v67, v0
	v_mov_b32_e32 v68, v0
	v_mov_b32_e32 v69, v0
	v_mov_b32_e32 v70, v0
	v_mov_b32_e32 v71, v0
	v_mov_b32_e32 v80, v0
	v_mov_b32_e32 v81, v0
	v_mov_b32_e32 v82, v0
	v_mov_b32_e32 v83, v0
	v_mov_b32_e32 v84, v0
	v_mov_b32_e32 v85, v0
	v_mov_b32_e32 v86, v0
	v_mov_b32_e32 v87, v0
	v_mov_b32_e32 v96, v0
	v_mov_b32_e32 v97, v0
	v_mov_b32_e32 v98, v0
	v_mov_b32_e32 v99, v0
	v_mov_b32_e32 v100, v0
	v_mov_b32_e32 v101, v0
	v_mov_b32_e32 v102, v0
	v_mov_b32_e32 v103, v0
	v_mov_b32_e32 v112, v0
	v_mov_b32_e32 v113, v0
	v_mov_b32_e32 v114, v0
	v_mov_b32_e32 v115, v0
	v_mov_b32_e32 v116, v0
	v_mov_b32_e32 v117, v0
	v_mov_b32_e32 v118, v0
	v_mov_b32_e32 v119, v0
	v_mov_b32_e32 v72, v0
	v_mov_b32_e32 v73, v0
	v_mov_b32_e32 v74, v0
	v_mov_b32_e32 v75, v0
	v_mov_b32_e32 v76, v0
	v_mov_b32_e32 v77, v0
	v_mov_b32_e32 v78, v0
	v_mov_b32_e32 v79, v0
	v_mov_b32_e32 v88, v0
	v_mov_b32_e32 v89, v0
	v_mov_b32_e32 v90, v0
	v_mov_b32_e32 v91, v0
	v_mov_b32_e32 v92, v0
	v_mov_b32_e32 v93, v0
	v_mov_b32_e32 v94, v0
	v_mov_b32_e32 v95, v0
	v_mov_b32_e32 v104, v0
	v_mov_b32_e32 v105, v0
	v_mov_b32_e32 v106, v0
	v_mov_b32_e32 v107, v0
	v_mov_b32_e32 v108, v0
	v_mov_b32_e32 v109, v0
	v_mov_b32_e32 v110, v0
	v_mov_b32_e32 v111, v0
	v_mov_b32_e32 v120, v0
	v_mov_b32_e32 v121, v0
	v_mov_b32_e32 v122, v0
	v_mov_b32_e32 v123, v0
	v_mov_b32_e32 v124, v0
	v_mov_b32_e32 v125, v0
	v_mov_b32_e32 v126, v0
	v_mov_b32_e32 v127, v0
	v_readfirstlane_b32 s98, v162
	s_nop 3
	s_cmp_ge_u32 s98, 0x100
	s_cbranch_scc0 .Lp7_prio_done
	s_setprio 1
.Lp7_prio_done:
.LBB0_583:
	s_add_u32 s12, s10, 0xfff80080
	s_addc_u32 s13, s11, -1
	s_add_i32 s17, 0, 0x10000
	s_cmp_eq_u32 s16, 28
	s_cselect_b32 s35, s27, s13
	s_cselect_b32 s34, s62, s12
	v_add_u32_e32 v132, s17, v159
	s_cselect_b32 s13, s25, vcc_hi
	s_cselect_b32 s12, s91, vcc_lo
	s_add_i32 s66, 0, 0x14000
	ds_read_b128 v[128:131], v132
	ds_read_b128 v[154:157], v132 offset:1024
	ds_read_b128 v[170:173], v132 offset:2048
	ds_read_b128 v[174:177], v132 offset:3072
	v_add_u32_e32 v132, s66, v159
	ds_read_b128 v[178:181], v132
	ds_read_b128 v[182:185], v132 offset:1024
	ds_read_b128 v[186:189], v132 offset:2048
	ds_read_b128 v[190:193], v132 offset:3072
	v_lshl_add_u64 v[226:227], s[10:11], 0, v[150:151]
	s_add_i32 m0, s41, 0xc000
	ds_read_b128 v[194:197], v161
	ds_read_b128 v[198:201], v161 offset:1024
	ds_read_b128 v[202:205], v161 offset:2048
	ds_read_b128 v[206:209], v161 offset:3072
	ds_read_b128 v[210:213], v161 offset:4096
	ds_read_b128 v[214:217], v161 offset:5120
	ds_read_b128 v[218:221], v161 offset:6144
	ds_read_b128 v[222:225], v161 offset:7168
	global_load_lds_dwordx4 v[226:227], off
	v_lshl_add_u64 v[226:227], s[10:11], 0, v[152:153]
	s_add_i32 m0, s41, 0xe000
	s_nop 0
	global_load_lds_dwordx4 v[226:227], off
	s_waitcnt vmcnt(8)
	s_waitcnt lgkmcnt(0)
	s_barrier
; #define PG8_STAGE(bufoff, gbase, voff) do { _Pragma("unroll") for (int _i = 0; _i < 2; ++_i) \
;         __builtin_amdgcn_global_load_lds((const unsigned*)((const char*)(gbase) + (voff)[_i]), (PG8_LAS unsigned*)(lds + (bufoff) + ldsw + _i * 8192), 16, 0, 0); } while (0)
; #define PG8_LDA(dst, b, h) do { _Pragma("unroll") for (int m = 0; m < 4; ++m) _Pragma("unroll") for (int k = 0; k < 2; ++k) dst[m][k] = *(const PG8_LAS bf16x8*)(lds + PG8_SA(b, h) + aoff + m * 2048 + k * 1024); } while (0)
; #define PG8_MMA(ai, bj, At, Bt) do { __builtin_amdgcn_s_setprio(1); _Pragma("unroll") for (int m = 0; m < 4; ++m) _Pragma("unroll") for (int n = 0; n < 2; ++n) _Pragma("unroll") for (int k = 0; k < 2; ++k) \
;         acc[ai][bj][m][n] = __builtin_amdgcn_mfma_f32_16x16x32_bf16(Bt[n][k], At[m][k], acc[ai][bj][m][n], 0, 0, 0); __builtin_amdgcn_s_setprio(0); } while (0)
; #define PG8_WAIT_V(n) asm volatile("s_waitcnt vmcnt(" #n ")" ::: "memory")
; #define PG8_WAIT_L(n) asm volatile("s_waitcnt lgkmcnt(" #n ")" ::: "memory")
; #define PG8_BAR __builtin_amdgcn_s_barrier()
; #define PG8_SCHED __builtin_amdgcn_sched_barrier(0)
; template <class Epi, class Sched, bool ALIGN_EPI = false, bool SP2 = false>
; __device__ __forceinline__ void gemm_phase(PG8_LAS unsigned char* lds, const Gemm g, const Sched& S, const Epi& E) {
;     ...
;             PG8_WAIT_V(8); PG8_WAIT_L(0); PG8_BAR; PG8_MMA(0, 0, At, B0); PG8_MMA(0, 1, At, B1); PG8_BAR; PG8_SCHED;
;             PG8_LDA(At, 0, 1); PG8_STAGE(PG8_SB(0, 0), b2, voffB); PG8_STAGE(PG8_SB(0, 1), b2 + hstep, voffB); PG8_STAGE(PG8_SA(0, 0), a2, voffA);
;             PG8_WAIT_V(8); PG8_WAIT_L(0); PG8_BAR; PG8_MMA(1, 0, At, B0); PG8_MMA(1, 1, At, B1); PG8_BAR; PG8_SCHED;
	s_waitcnt lgkmcnt(0)
	v_mfma_f32_16x16x32_bf16 v[124:127], v[128:131], v[194:197], v[124:127]
	v_mfma_f32_16x16x32_bf16 v[120:123], v[170:173], v[194:197], v[120:123]
	v_mfma_f32_16x16x32_bf16 v[108:111], v[128:131], v[202:205], v[108:111]
	v_mfma_f32_16x16x32_bf16 v[104:107], v[170:173], v[202:205], v[104:107]
	v_mfma_f32_16x16x32_bf16 v[92:95], v[128:131], v[210:213], v[92:95]
	v_mfma_f32_16x16x32_bf16 v[88:91], v[170:173], v[210:213], v[88:91]
	v_mfma_f32_16x16x32_bf16 v[76:79], v[128:131], v[218:221], v[76:79]
	v_mfma_f32_16x16x32_bf16 v[72:75], v[170:173], v[218:221], v[72:75]
	v_mfma_f32_16x16x32_bf16 v[124:127], v[154:157], v[198:201], v[124:127]
	v_mfma_f32_16x16x32_bf16 v[120:123], v[174:177], v[198:201], v[120:123]
	v_mfma_f32_16x16x32_bf16 v[108:111], v[154:157], v[206:209], v[108:111]
	v_mfma_f32_16x16x32_bf16 v[104:107], v[174:177], v[206:209], v[104:107]
	v_mfma_f32_16x16x32_bf16 v[92:95], v[154:157], v[214:217], v[92:95]
	v_mfma_f32_16x16x32_bf16 v[88:91], v[174:177], v[214:217], v[88:91]
	v_mfma_f32_16x16x32_bf16 v[76:79], v[154:157], v[222:225], v[76:79]
	v_mfma_f32_16x16x32_bf16 v[72:75], v[174:177], v[222:225], v[72:75]
	v_mfma_f32_16x16x32_bf16 v[116:119], v[178:181], v[194:197], v[116:119]
	v_mfma_f32_16x16x32_bf16 v[112:115], v[186:189], v[194:197], v[112:115]
	v_mfma_f32_16x16x32_bf16 v[100:103], v[178:181], v[202:205], v[100:103]
	v_mfma_f32_16x16x32_bf16 v[96:99], v[186:189], v[202:205], v[96:99]
	v_mfma_f32_16x16x32_bf16 v[84:87], v[178:181], v[210:213], v[84:87]
	v_mfma_f32_16x16x32_bf16 v[80:83], v[186:189], v[210:213], v[80:83]
	v_mfma_f32_16x16x32_bf16 v[68:71], v[178:181], v[218:221], v[68:71]
	v_mfma_f32_16x16x32_bf16 v[64:67], v[186:189], v[218:221], v[64:67]
	v_mfma_f32_16x16x32_bf16 v[116:119], v[182:185], v[198:201], v[116:119]
	v_mfma_f32_16x16x32_bf16 v[112:115], v[190:193], v[198:201], v[112:115]
	v_mfma_f32_16x16x32_bf16 v[100:103], v[182:185], v[206:209], v[100:103]
	v_mfma_f32_16x16x32_bf16 v[96:99], v[190:193], v[206:209], v[96:99]
	v_mfma_f32_16x16x32_bf16 v[84:87], v[182:185], v[214:217], v[84:87]
	v_mfma_f32_16x16x32_bf16 v[80:83], v[190:193], v[214:217], v[80:83]
	v_mfma_f32_16x16x32_bf16 v[68:71], v[182:185], v[222:225], v[68:71]
	v_mfma_f32_16x16x32_bf16 v[64:67], v[190:193], v[222:225], v[64:67]
	s_barrier
	s_add_i32 s17, s17, s40
	v_lshl_add_u64 v[226:227], s[12:13], 0, v[142:143]
	s_mov_b32 m0, s17
	ds_read_b128 v[194:197], v161 offset:16384
	ds_read_b128 v[198:201], v161 offset:17408
	ds_read_b128 v[202:205], v161 offset:18432
	ds_read_b128 v[206:209], v161 offset:19456
	ds_read_b128 v[210:213], v161 offset:20480
	ds_read_b128 v[214:217], v161 offset:21504
	ds_read_b128 v[218:221], v161 offset:22528
	ds_read_b128 v[222:225], v161 offset:23552
	global_load_lds_dwordx4 v[226:227], off
	s_add_i32 m0, s17, 0x2000
	s_add_u32 s64, s12, 0x80000
	v_lshl_add_u64 v[228:229], s[12:13], 0, v[138:139]
	s_addc_u32 s65, s13, 0
	s_add_i32 s17, s66, s40
	global_load_lds_dwordx4 v[228:229], off
	v_lshl_add_u64 v[230:231], s[64:65], 0, v[142:143]
	s_mov_b32 m0, s17
	v_lshl_add_u64 v[232:233], s[34:35], 0, v[140:141]
	global_load_lds_dwordx4 v[230:231], off
	v_lshl_add_u64 v[230:231], s[64:65], 0, v[138:139]
	s_add_i32 m0, s17, 0x2000
	s_nop 0
	global_load_lds_dwordx4 v[230:231], off
	v_lshl_add_u64 v[230:231], s[34:35], 0, v[144:145]
	s_mov_b32 m0, s41
	s_nop 0
	global_load_lds_dwordx4 v[230:231], off
	s_mov_b32 m0, s58
	s_nop 0
	global_load_lds_dwordx4 v[232:233], off
	s_waitcnt vmcnt(8)
	s_waitcnt lgkmcnt(0)
	s_barrier
	s_waitcnt lgkmcnt(0)
	v_mfma_f32_16x16x32_bf16 v[60:63], v[128:131], v[194:197], v[60:63]
	v_mfma_f32_16x16x32_bf16 v[56:59], v[170:173], v[194:197], v[56:59]
	v_mfma_f32_16x16x32_bf16 v[44:47], v[128:131], v[202:205], v[44:47]
	v_mfma_f32_16x16x32_bf16 v[40:43], v[170:173], v[202:205], v[40:43]
	v_mfma_f32_16x16x32_bf16 v[28:31], v[128:131], v[210:213], v[28:31]
	v_mfma_f32_16x16x32_bf16 v[24:27], v[170:173], v[210:213], v[24:27]
	v_mfma_f32_16x16x32_bf16 v[12:15], v[128:131], v[218:221], v[12:15]
	v_mfma_f32_16x16x32_bf16 v[8:11], v[170:173], v[218:221], v[8:11]
	v_mfma_f32_16x16x32_bf16 v[60:63], v[154:157], v[198:201], v[60:63]
	v_mfma_f32_16x16x32_bf16 v[56:59], v[174:177], v[198:201], v[56:59]
	v_mfma_f32_16x16x32_bf16 v[44:47], v[154:157], v[206:209], v[44:47]
	v_mfma_f32_16x16x32_bf16 v[40:43], v[174:177], v[206:209], v[40:43]
	v_mfma_f32_16x16x32_bf16 v[28:31], v[154:157], v[214:217], v[28:31]
	v_mfma_f32_16x16x32_bf16 v[24:27], v[174:177], v[214:217], v[24:27]
	v_mfma_f32_16x16x32_bf16 v[12:15], v[154:157], v[222:225], v[12:15]
	v_mfma_f32_16x16x32_bf16 v[8:11], v[174:177], v[222:225], v[8:11]
	v_mfma_f32_16x16x32_bf16 v[52:55], v[178:181], v[194:197], v[52:55]
	v_mfma_f32_16x16x32_bf16 v[48:51], v[186:189], v[194:197], v[48:51]
	v_mfma_f32_16x16x32_bf16 v[36:39], v[178:181], v[202:205], v[36:39]
	v_mfma_f32_16x16x32_bf16 v[32:35], v[186:189], v[202:205], v[32:35]
	v_mfma_f32_16x16x32_bf16 v[20:23], v[178:181], v[210:213], v[20:23]
	v_mfma_f32_16x16x32_bf16 v[16:19], v[186:189], v[210:213], v[16:19]
	v_mfma_f32_16x16x32_bf16 v[4:7], v[178:181], v[218:221], v[4:7]
	v_mfma_f32_16x16x32_bf16 v[0:3], v[186:189], v[218:221], v[0:3]
	v_mfma_f32_16x16x32_bf16 v[52:55], v[182:185], v[198:201], v[52:55]
	v_mfma_f32_16x16x32_bf16 v[48:51], v[190:193], v[198:201], v[48:51]
	v_mfma_f32_16x16x32_bf16 v[36:39], v[182:185], v[206:209], v[36:39]
	v_mfma_f32_16x16x32_bf16 v[32:35], v[190:193], v[206:209], v[32:35]
	v_mfma_f32_16x16x32_bf16 v[20:23], v[182:185], v[214:217], v[20:23]
	v_mfma_f32_16x16x32_bf16 v[16:19], v[190:193], v[214:217], v[16:19]
	v_mfma_f32_16x16x32_bf16 v[4:7], v[182:185], v[222:225], v[4:7]
	v_mfma_f32_16x16x32_bf16 v[0:3], v[190:193], v[222:225], v[0:3]
	s_barrier
; #define PG8_STAGE(bufoff, gbase, voff) do { _Pragma("unroll") for (int _i = 0; _i < 2; ++_i) \
;         __builtin_amdgcn_global_load_lds((const unsigned*)((const char*)(gbase) + (voff)[_i]), (PG8_LAS unsigned*)(lds + (bufoff) + ldsw + _i * 8192), 16, 0, 0); } while (0)
; #define PG8_LDA(dst, b, h) do { _Pragma("unroll") for (int m = 0; m < 4; ++m) _Pragma("unroll") for (int k = 0; k < 2; ++k) dst[m][k] = *(const PG8_LAS bf16x8*)(lds + PG8_SA(b, h) + aoff + m * 2048 + k * 1024); } while (0)
; #define PG8_LDB(dst, b, h) do { _Pragma("unroll") for (int n = 0; n < 2; ++n) _Pragma("unroll") for (int k = 0; k < 2; ++k) dst[n][k] = *(const PG8_LAS bf16x8*)(lds + PG8_SB(b, h) + boff + n * 2048 + k * 1024); } while (0)
; #define PG8_MMA(ai, bj, At, Bt) do { __builtin_amdgcn_s_setprio(1); _Pragma("unroll") for (int m = 0; m < 4; ++m) _Pragma("unroll") for (int n = 0; n < 2; ++n) _Pragma("unroll") for (int k = 0; k < 2; ++k) \
;         acc[ai][bj][m][n] = __builtin_amdgcn_mfma_f32_16x16x32_bf16(Bt[n][k], At[m][k], acc[ai][bj][m][n], 0, 0, 0); __builtin_amdgcn_s_setprio(0); } while (0)
; #define PG8_WAIT_V(n) asm volatile("s_waitcnt vmcnt(" #n ")" ::: "memory")
; #define PG8_WAIT_L(n) asm volatile("s_waitcnt lgkmcnt(" #n ")" ::: "memory")
; #define PG8_BAR __builtin_amdgcn_s_barrier()
; #define PG8_SCHED __builtin_amdgcn_sched_barrier(0)
; template <class Epi, class Sched, bool ALIGN_EPI = false, bool SP2 = false>
; __device__ __forceinline__ void gemm_phase(PG8_LAS unsigned char* lds, const Gemm g, const Sched& S, const Epi& E) {
;     ...
;             PG8_LDB(B0, 1, 0); PG8_LDB(B1, 1, 1); PG8_SCHED; PG8_LDA(At, 1, 0); PG8_STAGE(PG8_SA(0, 1), a2 + hstepA, voffA);
;             PG8_WAIT_V(8); PG8_WAIT_L(0); PG8_BAR; PG8_MMA(0, 0, At, B0); PG8_MMA(0, 1, At, B1); PG8_BAR; PG8_SCHED;
	s_add_i32 s17, 0, 0x18000
	v_add_u32_e32 v132, s17, v159
	s_add_i32 s64, 0, 0x1c000
	ds_read_b128 v[128:131], v132
	ds_read_b128 v[154:157], v132 offset:1024
	ds_read_b128 v[170:173], v132 offset:2048
	ds_read_b128 v[174:177], v132 offset:3072
	v_add_u32_e32 v132, s64, v159
	ds_read_b128 v[178:181], v132
	ds_read_b128 v[182:185], v132 offset:1024
	ds_read_b128 v[186:189], v132 offset:2048
	ds_read_b128 v[190:193], v132 offset:3072
	s_add_u32 s34, s34, 0x80000
	s_addc_u32 s35, s35, 0
	s_mov_b32 m0, s88
	v_lshl_add_u64 v[234:235], s[34:35], 0, v[144:145]
	ds_read_b128 v[194:197], v161 offset:32768
	ds_read_b128 v[198:201], v161 offset:33792
	ds_read_b128 v[202:205], v161 offset:34816
	ds_read_b128 v[206:209], v161 offset:35840
	ds_read_b128 v[210:213], v161 offset:36864
	ds_read_b128 v[214:217], v161 offset:37888
	ds_read_b128 v[218:221], v161 offset:38912
	ds_read_b128 v[222:225], v161 offset:39936
	global_load_lds_dwordx4 v[234:235], off
	v_lshl_add_u64 v[234:235], s[34:35], 0, v[140:141]
	s_mov_b32 m0, s89
	s_nop 0
	global_load_lds_dwordx4 v[234:235], off
	s_waitcnt vmcnt(8)
	s_waitcnt lgkmcnt(0)
	s_barrier
	s_waitcnt lgkmcnt(0)
	v_mfma_f32_16x16x32_bf16 v[124:127], v[128:131], v[194:197], v[124:127]
	v_mfma_f32_16x16x32_bf16 v[120:123], v[170:173], v[194:197], v[120:123]
	v_mfma_f32_16x16x32_bf16 v[108:111], v[128:131], v[202:205], v[108:111]
	v_mfma_f32_16x16x32_bf16 v[104:107], v[170:173], v[202:205], v[104:107]
	v_mfma_f32_16x16x32_bf16 v[92:95], v[128:131], v[210:213], v[92:95]
	v_mfma_f32_16x16x32_bf16 v[88:91], v[170:173], v[210:213], v[88:91]
	v_mfma_f32_16x16x32_bf16 v[76:79], v[128:131], v[218:221], v[76:79]
	v_mfma_f32_16x16x32_bf16 v[72:75], v[170:173], v[218:221], v[72:75]
	v_mfma_f32_16x16x32_bf16 v[124:127], v[154:157], v[198:201], v[124:127]
	v_mfma_f32_16x16x32_bf16 v[120:123], v[174:177], v[198:201], v[120:123]
	v_mfma_f32_16x16x32_bf16 v[108:111], v[154:157], v[206:209], v[108:111]
	v_mfma_f32_16x16x32_bf16 v[104:107], v[174:177], v[206:209], v[104:107]
	v_mfma_f32_16x16x32_bf16 v[92:95], v[154:157], v[214:217], v[92:95]
	v_mfma_f32_16x16x32_bf16 v[88:91], v[174:177], v[214:217], v[88:91]
	v_mfma_f32_16x16x32_bf16 v[76:79], v[154:157], v[222:225], v[76:79]
	v_mfma_f32_16x16x32_bf16 v[72:75], v[174:177], v[222:225], v[72:75]
	v_mfma_f32_16x16x32_bf16 v[116:119], v[178:181], v[194:197], v[116:119]
	v_mfma_f32_16x16x32_bf16 v[112:115], v[186:189], v[194:197], v[112:115]
	v_mfma_f32_16x16x32_bf16 v[100:103], v[178:181], v[202:205], v[100:103]
	v_mfma_f32_16x16x32_bf16 v[96:99], v[186:189], v[202:205], v[96:99]
	v_mfma_f32_16x16x32_bf16 v[84:87], v[178:181], v[210:213], v[84:87]
	v_mfma_f32_16x16x32_bf16 v[80:83], v[186:189], v[210:213], v[80:83]
	v_mfma_f32_16x16x32_bf16 v[68:71], v[178:181], v[218:221], v[68:71]
	v_mfma_f32_16x16x32_bf16 v[64:67], v[186:189], v[218:221], v[64:67]
	v_mfma_f32_16x16x32_bf16 v[116:119], v[182:185], v[198:201], v[116:119]
	v_mfma_f32_16x16x32_bf16 v[112:115], v[190:193], v[198:201], v[112:115]
	v_mfma_f32_16x16x32_bf16 v[100:103], v[182:185], v[206:209], v[100:103]
	v_mfma_f32_16x16x32_bf16 v[96:99], v[190:193], v[206:209], v[96:99]
	v_mfma_f32_16x16x32_bf16 v[84:87], v[182:185], v[214:217], v[84:87]
	v_mfma_f32_16x16x32_bf16 v[80:83], v[190:193], v[214:217], v[80:83]
	v_mfma_f32_16x16x32_bf16 v[68:71], v[182:185], v[222:225], v[68:71]
	v_mfma_f32_16x16x32_bf16 v[64:67], v[190:193], v[222:225], v[64:67]
	s_barrier
; #define PG8_STAGE(bufoff, gbase, voff) do { _Pragma("unroll") for (int _i = 0; _i < 2; ++_i) \
;         __builtin_amdgcn_global_load_lds((const unsigned*)((const char*)(gbase) + (voff)[_i]), (PG8_LAS unsigned*)(lds + (bufoff) + ldsw + _i * 8192), 16, 0, 0); } while (0)
; #define PG8_LDA(dst, b, h) do { _Pragma("unroll") for (int m = 0; m < 4; ++m) _Pragma("unroll") for (int k = 0; k < 2; ++k) dst[m][k] = *(const PG8_LAS bf16x8*)(lds + PG8_SA(b, h) + aoff + m * 2048 + k * 1024); } while (0)
; #define PG8_MMA(ai, bj, At, Bt) do { __builtin_amdgcn_s_setprio(1); _Pragma("unroll") for (int m = 0; m < 4; ++m) _Pragma("unroll") for (int n = 0; n < 2; ++n) _Pragma("unroll") for (int k = 0; k < 2; ++k) \
;         acc[ai][bj][m][n] = __builtin_amdgcn_mfma_f32_16x16x32_bf16(Bt[n][k], At[m][k], acc[ai][bj][m][n], 0, 0, 0); __builtin_amdgcn_s_setprio(0); } while (0)
; #define PG8_WAIT_V(n) asm volatile("s_waitcnt vmcnt(" #n ")" ::: "memory")
; #define PG8_WAIT_L(n) asm volatile("s_waitcnt lgkmcnt(" #n ")" ::: "memory")
; #define PG8_BAR __builtin_amdgcn_s_barrier()
; #define PG8_SCHED __builtin_amdgcn_sched_barrier(0)
; template <class Epi, class Sched, bool ALIGN_EPI = false, bool SP2 = false>
; __device__ __forceinline__ void gemm_phase(PG8_LAS unsigned char* lds, const Gemm g, const Sched& S, const Epi& E) {
;     ...
;         for (int t = 0; t < nt; t += 2) {
;     ...
;             PG8_LDA(At, 1, 1); PG8_STAGE(PG8_SB(1, 0), b3, voffB); PG8_STAGE(PG8_SB(1, 1), b3 + hstep, voffB); PG8_STAGE(PG8_SA(1, 0), a3, voffA);
;             PG8_WAIT_V(8); PG8_WAIT_L(0); PG8_BAR; PG8_MMA(1, 0, At, B0); PG8_MMA(1, 1, At, B1); PG8_BAR; PG8_SCHED;
	s_add_i32 s17, s17, s40
	v_lshl_add_u64 v[226:227], v[226:227], 0, s[68:69]
	s_mov_b32 m0, s17
	ds_read_b128 v[194:197], v161 offset:49152
	ds_read_b128 v[198:201], v161 offset:50176
	ds_read_b128 v[202:205], v161 offset:51200
	ds_read_b128 v[206:209], v161 offset:52224
	ds_read_b128 v[210:213], v161 offset:53248
	ds_read_b128 v[214:217], v161 offset:54272
	ds_read_b128 v[218:221], v161 offset:55296
	ds_read_b128 v[222:225], v161 offset:56320
	global_load_lds_dwordx4 v[226:227], off
	s_add_i32 m0, s17, 0x2000
	s_add_u32 s12, s12, 0x80080
	v_lshl_add_u64 v[226:227], v[228:229], 0, s[68:69]
	s_addc_u32 s13, s13, 0
	s_add_i32 s17, s64, s40
	global_load_lds_dwordx4 v[226:227], off
	v_lshl_add_u64 v[226:227], s[12:13], 0, v[142:143]
	s_mov_b32 m0, s17
	s_nop 0
	global_load_lds_dwordx4 v[226:227], off
	v_lshl_add_u64 v[226:227], s[12:13], 0, v[138:139]
	s_add_i32 m0, s17, 0x2000
	s_nop 0
	global_load_lds_dwordx4 v[226:227], off
	v_lshl_add_u64 v[226:227], v[230:231], 0, s[68:69]
	s_mov_b32 m0, s76
	s_nop 0
	global_load_lds_dwordx4 v[226:227], off
	v_lshl_add_u64 v[226:227], v[232:233], 0, s[68:69]
	s_mov_b32 m0, s77
	s_nop 0
	global_load_lds_dwordx4 v[226:227], off
	s_waitcnt vmcnt(8)
	s_waitcnt lgkmcnt(0)
	s_barrier
	s_waitcnt lgkmcnt(0)
	v_mfma_f32_16x16x32_bf16 v[60:63], v[128:131], v[194:197], v[60:63]
	v_mfma_f32_16x16x32_bf16 v[56:59], v[170:173], v[194:197], v[56:59]
	v_mfma_f32_16x16x32_bf16 v[44:47], v[128:131], v[202:205], v[44:47]
	v_mfma_f32_16x16x32_bf16 v[40:43], v[170:173], v[202:205], v[40:43]
	v_mfma_f32_16x16x32_bf16 v[28:31], v[128:131], v[210:213], v[28:31]
	v_mfma_f32_16x16x32_bf16 v[24:27], v[170:173], v[210:213], v[24:27]
	v_mfma_f32_16x16x32_bf16 v[12:15], v[128:131], v[218:221], v[12:15]
	v_mfma_f32_16x16x32_bf16 v[8:11], v[170:173], v[218:221], v[8:11]
	v_mfma_f32_16x16x32_bf16 v[60:63], v[154:157], v[198:201], v[60:63]
	v_mfma_f32_16x16x32_bf16 v[56:59], v[174:177], v[198:201], v[56:59]
	v_mfma_f32_16x16x32_bf16 v[44:47], v[154:157], v[206:209], v[44:47]
	v_mfma_f32_16x16x32_bf16 v[40:43], v[174:177], v[206:209], v[40:43]
	v_mfma_f32_16x16x32_bf16 v[28:31], v[154:157], v[214:217], v[28:31]
	v_mfma_f32_16x16x32_bf16 v[24:27], v[174:177], v[214:217], v[24:27]
	v_mfma_f32_16x16x32_bf16 v[12:15], v[154:157], v[222:225], v[12:15]
	v_mfma_f32_16x16x32_bf16 v[8:11], v[174:177], v[222:225], v[8:11]
	v_mfma_f32_16x16x32_bf16 v[52:55], v[178:181], v[194:197], v[52:55]
	v_mfma_f32_16x16x32_bf16 v[48:51], v[186:189], v[194:197], v[48:51]
	v_mfma_f32_16x16x32_bf16 v[36:39], v[178:181], v[202:205], v[36:39]
	v_mfma_f32_16x16x32_bf16 v[32:35], v[186:189], v[202:205], v[32:35]
	v_mfma_f32_16x16x32_bf16 v[20:23], v[178:181], v[210:213], v[20:23]
	v_mfma_f32_16x16x32_bf16 v[16:19], v[186:189], v[210:213], v[16:19]
	v_mfma_f32_16x16x32_bf16 v[4:7], v[178:181], v[218:221], v[4:7]
	v_mfma_f32_16x16x32_bf16 v[0:3], v[186:189], v[218:221], v[0:3]
	v_mfma_f32_16x16x32_bf16 v[52:55], v[182:185], v[198:201], v[52:55]
	v_mfma_f32_16x16x32_bf16 v[48:51], v[190:193], v[198:201], v[48:51]
	v_mfma_f32_16x16x32_bf16 v[36:39], v[182:185], v[206:209], v[36:39]
	v_mfma_f32_16x16x32_bf16 v[32:35], v[190:193], v[206:209], v[32:35]
	v_mfma_f32_16x16x32_bf16 v[20:23], v[182:185], v[214:217], v[20:23]
	v_mfma_f32_16x16x32_bf16 v[16:19], v[190:193], v[214:217], v[16:19]
	v_mfma_f32_16x16x32_bf16 v[4:7], v[182:185], v[222:225], v[4:7]
	v_mfma_f32_16x16x32_bf16 v[0:3], v[190:193], v[222:225], v[0:3]
	s_barrier
	s_add_i32 s16, s16, 2
	s_add_u32 s10, s10, 0x100
	s_addc_u32 s11, s11, 0
	s_add_u32 vcc_lo, vcc_lo, 0x100
	s_addc_u32 vcc_hi, vcc_hi, 0
	s_cmp_gt_u32 s16, 29
	s_cbranch_scc0 .LBB0_583
	s_setprio 0
	s_and_b64 vcc, exec, s[18:19]
	s_cbranch_vccnz .LBB0_588
	v_lshl_add_u32 v154, s63, 8, v158
	s_cmp_gt_i32 s81, 31
	s_mov_b64 s[10:11], -1
	s_cbranch_scc1 .LBB0_589
